# DA pipelined loop + softmax row sums by 4 x v_mfma_f32_16x16x32_bf16 per tile (P as A, 0/1 indicator as B) instead of 32 v_add; l kept in 4 accumulator regs, folded into the per-row table at pass end
# speedup vs baseline: 1.0085x; 1.0061x over previous
.LBB0_598:
	v_add_f32_e32 v184, v18, v19
	v_lshlrev_b32_e32 v18, 1, v50
	v_and_b32_e32 v18, 32, v18
	v_and_or_b32 v18, v51, s66, v18
	v_and_b32_e32 v19, 0x100, v52
	v_fmac_f32_e32 v184, 0, v56
	v_or3_b32 v187, v18, v19, v53
	s_add_i32 s35, 0, 0xc000
	v_cmp_gt_u32_e64 s[4:5], 32, v50
	v_lshl_add_u32 v186, v54, 2, s18
	v_lshlrev_b32_e32 v185, 4, v55
	v_mov_b64_e32 v[32:33], v[16:17]
	v_mov_b64_e32 v[48:49], v[16:17]
	v_mov_b64_e32 v[64:65], v[16:17]
	s_mov_b32 s96, 1
	v_add_u32_e32 v193, s35, v187
	s_lshl_b32 s97, s12, 8
	s_mov_b32 s12, 0x8000
	s_movk_i32 s74, 0x4000
	s_mov_b32 s0, 0
	v_mov_b64_e32 v[30:31], v[14:15]
	v_mov_b64_e32 v[28:29], v[12:13]
	v_mov_b64_e32 v[26:27], v[10:11]
	v_mov_b64_e32 v[24:25], v[8:9]
	v_mov_b64_e32 v[22:23], v[6:7]
	v_mov_b64_e32 v[20:21], v[4:5]
	v_mov_b64_e32 v[18:19], v[2:3]
	v_mov_b64_e32 v[46:47], v[14:15]
	v_mov_b64_e32 v[44:45], v[12:13]
	v_mov_b64_e32 v[42:43], v[10:11]
	v_mov_b64_e32 v[40:41], v[8:9]
	v_mov_b64_e32 v[38:39], v[6:7]
	v_mov_b64_e32 v[36:37], v[4:5]
	v_mov_b64_e32 v[34:35], v[2:3]
	v_mov_b64_e32 v[62:63], v[14:15]
	v_mov_b64_e32 v[60:61], v[12:13]
	v_mov_b64_e32 v[58:59], v[10:11]
	v_mov_b64_e32 v[56:57], v[8:9]
	v_mov_b64_e32 v[54:55], v[6:7]
	v_mov_b64_e32 v[52:53], v[4:5]
	v_mov_b64_e32 v[50:51], v[2:3]
	s_mov_b32 s75, s74
	s_mov_b32 s74, s0
	v_add_u32_e32 v238, s74, v193
	v_mbcnt_lo_u32_b32 v242, -1, 0
	v_mbcnt_hi_u32_b32 v242, -1, v242
	v_and_b32_e32 v243, 7, v242
	v_lshrrev_b32_e32 v252, 4, v242
	v_lshrrev_b32_e32 v244, 3, v242
	v_xor_b32_e32 v244, v244, v252
	v_and_b32_e32 v244, 1, v244
	v_cmp_eq_u32_e64 s[100:101], 0, v244
	v_mov_b32_e32 v245, 0x3f803f80
	s_nop 1
	v_cndmask_b32_e64 v248, 0, v245, s[100:101]
	v_mov_b32_e32 v249, v248
	v_mov_b32_e32 v250, v248
	v_mov_b32_e32 v251, v248
	v_lshlrev_b32_e32 v252, 4, v252
	v_and_b32_e32 v244, 8, v242
	v_lshl_add_u32 v252, v244, 3, v252
	v_mov_b32_e32 v244, 0
	v_mov_b32_e32 v245, 0
	v_mov_b32_e32 v246, 0
	v_mov_b32_e32 v247, 0
	s_barrier
	s_setprio 3
	ds_read_b128 v[82:85], v188 offset:40960
	ds_read_b128 v[210:213], v188 offset:45056
	ds_read_b128 v[214:217], v189 offset:40960
	ds_read_b128 v[218:221], v189 offset:45056
	ds_read_b128 v[222:225], v190 offset:40960
	ds_read_b128 v[226:229], v190 offset:45056
	ds_read_b128 v[230:233], v191 offset:40960
	ds_read_b128 v[234:237], v191 offset:45056
	ds_read_b64_tr_b16 v[194:195], v238 offset:0
	ds_read_b64_tr_b16 v[196:197], v238 offset:0x800
	ds_read_b64_tr_b16 v[198:199], v238 offset:0x1000
	ds_read_b64_tr_b16 v[200:201], v238 offset:0x1800
	s_waitcnt lgkmcnt(11)
	v_mfma_f32_32x32x16_bf16 v[98:113], v[82:85], v[126:129], v[66:81]
	s_waitcnt lgkmcnt(10)
	v_mfma_f32_32x32x16_bf16 v[82:97], v[210:213], v[126:129], v[66:81]
	ds_read_b64_tr_b16 v[202:203], v238 offset:0x2000
	ds_read_b64_tr_b16 v[204:205], v238 offset:0x2800
	ds_read_b64_tr_b16 v[206:207], v238 offset:0x3000
	ds_read_b64_tr_b16 v[208:209], v238 offset:0x3800
	s_waitcnt lgkmcnt(13)
	v_mfma_f32_32x32x16_bf16 v[98:113], v[214:217], v[122:125], v[98:113]
	s_waitcnt lgkmcnt(12)
	v_mfma_f32_32x32x16_bf16 v[82:97], v[218:221], v[122:125], v[82:97]
	s_waitcnt lgkmcnt(11)
	v_mfma_f32_32x32x16_bf16 v[98:113], v[222:225], v[118:121], v[98:113]
	s_waitcnt lgkmcnt(10)
	v_mfma_f32_32x32x16_bf16 v[82:97], v[226:229], v[118:121], v[82:97]
	s_waitcnt lgkmcnt(9)
	v_mfma_f32_32x32x16_bf16 v[98:113], v[230:233], v[114:117], v[98:113]
	s_waitcnt lgkmcnt(8)
	v_mfma_f32_32x32x16_bf16 v[82:97], v[234:237], v[114:117], v[82:97]
	ds_read_b64_tr_b16 v[210:211], v238 offset:0x200
	ds_read_b64_tr_b16 v[212:213], v238 offset:0xa00
	ds_read_b64_tr_b16 v[214:215], v238 offset:0x1200
	ds_read_b64_tr_b16 v[216:217], v238 offset:0x1a00
	ds_read_b64_tr_b16 v[218:219], v238 offset:0x2200
	ds_read_b64_tr_b16 v[220:221], v238 offset:0x2a00
	ds_read_b64_tr_b16 v[222:223], v238 offset:0x3200
	ds_read_b64_tr_b16 v[224:225], v238 offset:0x3a00
	s_waitcnt lgkmcnt(14)
	v_mfma_f32_32x32x16_bf16 v[50:65], v[142:145], v[194:197], v[50:65]
	s_waitcnt lgkmcnt(12)
	v_mfma_f32_32x32x16_bf16 v[50:65], v[138:141], v[198:201], v[50:65]
	s_waitcnt lgkmcnt(10)
	v_mfma_f32_32x32x16_bf16 v[50:65], v[134:137], v[202:205], v[50:65]
	s_waitcnt lgkmcnt(8)
	v_mfma_f32_32x32x16_bf16 v[50:65], v[130:133], v[206:209], v[50:65]
	ds_read_b64_tr_b16 v[194:195], v238 offset:0x400
	ds_read_b64_tr_b16 v[196:197], v238 offset:0xc00
	ds_read_b64_tr_b16 v[198:199], v238 offset:0x1400
	ds_read_b64_tr_b16 v[200:201], v238 offset:0x1c00
	ds_read_b64_tr_b16 v[202:203], v238 offset:0x2400
	ds_read_b64_tr_b16 v[204:205], v238 offset:0x2c00
	ds_read_b64_tr_b16 v[206:207], v238 offset:0x3400
	ds_read_b64_tr_b16 v[208:209], v238 offset:0x3c00
	s_waitcnt lgkmcnt(14)
	v_mfma_f32_32x32x16_bf16 v[34:49], v[142:145], v[210:213], v[34:49]
	s_waitcnt lgkmcnt(12)
	v_mfma_f32_32x32x16_bf16 v[34:49], v[138:141], v[214:217], v[34:49]
	s_waitcnt lgkmcnt(10)
	v_mfma_f32_32x32x16_bf16 v[34:49], v[134:137], v[218:221], v[34:49]
	s_waitcnt lgkmcnt(8)
	v_mfma_f32_32x32x16_bf16 v[34:49], v[130:133], v[222:225], v[34:49]
	ds_read_b64_tr_b16 v[210:211], v238 offset:0x600
	ds_read_b64_tr_b16 v[212:213], v238 offset:0xe00
	ds_read_b64_tr_b16 v[214:215], v238 offset:0x1600
	ds_read_b64_tr_b16 v[216:217], v238 offset:0x1e00
	ds_read_b64_tr_b16 v[218:219], v238 offset:0x2600
	ds_read_b64_tr_b16 v[220:221], v238 offset:0x2e00
	ds_read_b64_tr_b16 v[222:223], v238 offset:0x3600
	ds_read_b64_tr_b16 v[224:225], v238 offset:0x3e00
	s_waitcnt lgkmcnt(14)
	v_mfma_f32_32x32x16_bf16 v[18:33], v[142:145], v[194:197], v[18:33]
	s_waitcnt lgkmcnt(12)
	v_mfma_f32_32x32x16_bf16 v[18:33], v[138:141], v[198:201], v[18:33]
	s_waitcnt lgkmcnt(10)
	v_mfma_f32_32x32x16_bf16 v[18:33], v[134:137], v[202:205], v[18:33]
	s_waitcnt lgkmcnt(8)
	v_mfma_f32_32x32x16_bf16 v[18:33], v[130:133], v[206:209], v[18:33]
	s_waitcnt lgkmcnt(6)
	v_mfma_f32_32x32x16_bf16 v[2:17], v[142:145], v[210:213], v[2:17]
	s_waitcnt lgkmcnt(4)
	v_mfma_f32_32x32x16_bf16 v[2:17], v[138:141], v[214:217], v[2:17]
	s_waitcnt lgkmcnt(2)
	v_mfma_f32_32x32x16_bf16 v[2:17], v[134:137], v[218:221], v[2:17]
	s_waitcnt lgkmcnt(0)
	v_mfma_f32_32x32x16_bf16 v[2:17], v[130:133], v[222:225], v[2:17]
	s_branch .Lda_after_ma
.LBB0_599:
	s_barrier
	s_setprio 3
	ds_read_b64_tr_b16 v[194:195], v238 offset:0
	ds_read_b64_tr_b16 v[196:197], v238 offset:0x800
	ds_read_b64_tr_b16 v[198:199], v238 offset:0x200
	ds_read_b64_tr_b16 v[200:201], v238 offset:0xa00
	ds_read_b64_tr_b16 v[202:203], v238 offset:0x400
	ds_read_b64_tr_b16 v[204:205], v238 offset:0xc00
	ds_read_b64_tr_b16 v[206:207], v238 offset:0x600
	ds_read_b64_tr_b16 v[208:209], v238 offset:0xe00
	ds_read_b128 v[226:229], v188 offset:45056
	ds_read_b128 v[230:233], v189 offset:40960
	ds_read_b128 v[234:237], v189 offset:45056
	s_waitcnt lgkmcnt(9)
	v_mfma_f32_32x32x16_bf16 v[50:65], v[142:145], v[194:197], v[50:65]
	v_cvt_pk_bf16_f32 v138, v106, v107
	ds_read_b64_tr_b16 v[210:211], v238 offset:0x1000
	ds_read_b64_tr_b16 v[212:213], v238 offset:0x1800
	s_waitcnt lgkmcnt(9)
	v_mfma_f32_32x32x16_bf16 v[34:49], v[142:145], v[198:201], v[34:49]
	v_cvt_pk_bf16_f32 v139, v108, v109
	ds_read_b64_tr_b16 v[214:215], v238 offset:0x1200
	ds_read_b64_tr_b16 v[216:217], v238 offset:0x1a00
	s_waitcnt lgkmcnt(9)
	v_mfma_f32_32x32x16_bf16 v[18:33], v[142:145], v[202:205], v[18:33]
	v_cvt_pk_bf16_f32 v140, v110, v111
	ds_read_b64_tr_b16 v[218:219], v238 offset:0x1400
	ds_read_b64_tr_b16 v[220:221], v238 offset:0x1c00
	s_waitcnt lgkmcnt(9)
	v_mfma_f32_32x32x16_bf16 v[2:17], v[142:145], v[206:209], v[2:17]
	v_cvt_pk_bf16_f32 v141, v112, v113
	ds_read_b64_tr_b16 v[222:223], v238 offset:0x1600
	ds_read_b64_tr_b16 v[224:225], v238 offset:0x1e00
	v_mfma_f32_16x16x32_bf16 v[244:247], v[142:145], v[248:251], v[244:247]
	s_waitcnt lgkmcnt(6)
	v_mfma_f32_32x32x16_bf16 v[50:65], v[138:141], v[210:213], v[50:65]
	v_cvt_pk_bf16_f32 v134, v82, v83
	ds_read_b64_tr_b16 v[194:195], v238 offset:0x2000
	ds_read_b64_tr_b16 v[196:197], v238 offset:0x2800
	s_waitcnt lgkmcnt(6)
	v_mfma_f32_32x32x16_bf16 v[34:49], v[138:141], v[214:217], v[34:49]
	v_cvt_pk_bf16_f32 v135, v84, v85
	ds_read_b64_tr_b16 v[198:199], v238 offset:0x2200
	ds_read_b64_tr_b16 v[200:201], v238 offset:0x2a00
	s_waitcnt lgkmcnt(6)
	v_mfma_f32_32x32x16_bf16 v[18:33], v[138:141], v[218:221], v[18:33]
	v_cvt_pk_bf16_f32 v136, v86, v87
	ds_read_b64_tr_b16 v[202:203], v238 offset:0x2400
	ds_read_b64_tr_b16 v[204:205], v238 offset:0x2c00
	s_waitcnt lgkmcnt(6)
	v_mfma_f32_32x32x16_bf16 v[2:17], v[138:141], v[222:225], v[2:17]
	v_cvt_pk_bf16_f32 v137, v88, v89
	ds_read_b64_tr_b16 v[206:207], v238 offset:0x2600
	ds_read_b64_tr_b16 v[208:209], v238 offset:0x2e00
	v_mfma_f32_16x16x32_bf16 v[244:247], v[138:141], v[248:251], v[244:247]
	s_waitcnt lgkmcnt(6)
	v_mfma_f32_32x32x16_bf16 v[50:65], v[134:137], v[194:197], v[50:65]
	v_cvt_pk_bf16_f32 v130, v90, v91
	ds_read_b64_tr_b16 v[210:211], v238 offset:0x3000
	ds_read_b64_tr_b16 v[212:213], v238 offset:0x3800
	s_waitcnt lgkmcnt(6)
	v_mfma_f32_32x32x16_bf16 v[34:49], v[134:137], v[198:201], v[34:49]
	v_cvt_pk_bf16_f32 v131, v92, v93
	ds_read_b64_tr_b16 v[214:215], v238 offset:0x3200
	ds_read_b64_tr_b16 v[216:217], v238 offset:0x3a00
	s_waitcnt lgkmcnt(6)
	v_mfma_f32_32x32x16_bf16 v[18:33], v[134:137], v[202:205], v[18:33]
	v_cvt_pk_bf16_f32 v132, v94, v95
	ds_read_b64_tr_b16 v[218:219], v238 offset:0x3400
	ds_read_b64_tr_b16 v[220:221], v238 offset:0x3c00
	s_waitcnt lgkmcnt(6)
	v_mfma_f32_32x32x16_bf16 v[2:17], v[134:137], v[206:209], v[2:17]
	v_cvt_pk_bf16_f32 v133, v96, v97
	ds_read_b64_tr_b16 v[222:223], v238 offset:0x3600
	ds_read_b64_tr_b16 v[224:225], v238 offset:0x3e00
	v_mfma_f32_16x16x32_bf16 v[244:247], v[134:137], v[248:251], v[244:247]
	s_waitcnt lgkmcnt(6)
	v_mfma_f32_32x32x16_bf16 v[50:65], v[130:133], v[210:213], v[50:65]
	ds_read_b128 v[82:85], v188 offset:40960
	ds_read_b128 v[194:197], v190 offset:40960
	s_waitcnt lgkmcnt(6)
	v_mfma_f32_32x32x16_bf16 v[34:49], v[130:133], v[214:217], v[34:49]
	ds_read_b128 v[198:201], v190 offset:45056
	s_waitcnt lgkmcnt(5)
	v_mfma_f32_32x32x16_bf16 v[18:33], v[130:133], v[218:221], v[18:33]
	ds_read_b128 v[202:205], v191 offset:40960
	s_waitcnt lgkmcnt(4)
	v_mfma_f32_32x32x16_bf16 v[2:17], v[130:133], v[222:225], v[2:17]
	ds_read_b128 v[206:209], v191 offset:45056
	v_mfma_f32_16x16x32_bf16 v[244:247], v[130:133], v[248:251], v[244:247]
	s_waitcnt lgkmcnt(4)
	v_mfma_f32_32x32x16_bf16 v[98:113], v[82:85], v[126:129], v[66:81]
	v_mfma_f32_32x32x16_bf16 v[82:97], v[226:229], v[126:129], v[66:81]
	v_mfma_f32_32x32x16_bf16 v[98:113], v[230:233], v[122:125], v[98:113]
	v_mfma_f32_32x32x16_bf16 v[82:97], v[234:237], v[122:125], v[82:97]
	s_waitcnt lgkmcnt(3)
	v_mfma_f32_32x32x16_bf16 v[98:113], v[194:197], v[118:121], v[98:113]
	s_waitcnt lgkmcnt(2)
	v_mfma_f32_32x32x16_bf16 v[82:97], v[198:201], v[118:121], v[82:97]
	s_waitcnt lgkmcnt(1)
	v_mfma_f32_32x32x16_bf16 v[98:113], v[202:205], v[114:117], v[98:113]
	s_waitcnt lgkmcnt(0)
	v_mfma_f32_32x32x16_bf16 v[82:97], v[206:209], v[114:117], v[82:97]

.LBB0_612:
	s_barrier
	s_setprio 3
	v_add_u32_e32 v197, s75, v193
	ds_read_b64_tr_b16 v[198:199], v197 offset:0
	ds_read_b64_tr_b16 v[200:201], v197 offset:0x800
	ds_read_b64_tr_b16 v[202:203], v197 offset:0x200
	ds_read_b64_tr_b16 v[204:205], v197 offset:0xa00
	ds_read_b64_tr_b16 v[206:207], v197 offset:0x400
	ds_read_b64_tr_b16 v[208:209], v197 offset:0xc00
	ds_read_b64_tr_b16 v[210:211], v197 offset:0x600
	ds_read_b64_tr_b16 v[212:213], v197 offset:0xe00
	ds_read_b128 v[230:233], v188 offset:36864
	ds_read_b128 v[234:237], v189 offset:32768
	ds_read_b128 v[238:241], v189 offset:36864
	s_waitcnt lgkmcnt(9)
	v_mfma_f32_32x32x16_bf16 v[50:65], v[142:145], v[198:201], v[50:65]
	v_cvt_pk_bf16_f32 v138, v106, v107
	ds_read_b64_tr_b16 v[214:215], v197 offset:0x1000
	ds_read_b64_tr_b16 v[216:217], v197 offset:0x1800
	s_waitcnt lgkmcnt(9)
	v_mfma_f32_32x32x16_bf16 v[34:49], v[142:145], v[202:205], v[34:49]
	v_cvt_pk_bf16_f32 v139, v108, v109
	ds_read_b64_tr_b16 v[218:219], v197 offset:0x1200
	ds_read_b64_tr_b16 v[220:221], v197 offset:0x1a00
	s_waitcnt lgkmcnt(9)
	v_mfma_f32_32x32x16_bf16 v[18:33], v[142:145], v[206:209], v[18:33]
	v_cvt_pk_bf16_f32 v140, v110, v111
	ds_read_b64_tr_b16 v[222:223], v197 offset:0x1400
	ds_read_b64_tr_b16 v[224:225], v197 offset:0x1c00
	s_waitcnt lgkmcnt(9)
	v_mfma_f32_32x32x16_bf16 v[2:17], v[142:145], v[210:213], v[2:17]
	v_cvt_pk_bf16_f32 v141, v112, v113
	ds_read_b64_tr_b16 v[226:227], v197 offset:0x1600
	ds_read_b64_tr_b16 v[228:229], v197 offset:0x1e00
	v_mfma_f32_16x16x32_bf16 v[244:247], v[142:145], v[248:251], v[244:247]
	s_waitcnt lgkmcnt(6)
	v_mfma_f32_32x32x16_bf16 v[50:65], v[138:141], v[214:217], v[50:65]
	v_cvt_pk_bf16_f32 v134, v82, v83
	ds_read_b64_tr_b16 v[198:199], v197 offset:0x2000
	ds_read_b64_tr_b16 v[200:201], v197 offset:0x2800
	s_waitcnt lgkmcnt(6)
	v_mfma_f32_32x32x16_bf16 v[34:49], v[138:141], v[218:221], v[34:49]
	v_cvt_pk_bf16_f32 v135, v84, v85
	ds_read_b64_tr_b16 v[202:203], v197 offset:0x2200
	ds_read_b64_tr_b16 v[204:205], v197 offset:0x2a00
	s_waitcnt lgkmcnt(6)
	v_mfma_f32_32x32x16_bf16 v[18:33], v[138:141], v[222:225], v[18:33]
	v_cvt_pk_bf16_f32 v136, v86, v87
	ds_read_b64_tr_b16 v[206:207], v197 offset:0x2400
	ds_read_b64_tr_b16 v[208:209], v197 offset:0x2c00
	s_waitcnt lgkmcnt(6)
	v_mfma_f32_32x32x16_bf16 v[2:17], v[138:141], v[226:229], v[2:17]
	v_cvt_pk_bf16_f32 v137, v88, v89
	ds_read_b64_tr_b16 v[210:211], v197 offset:0x2600
	ds_read_b64_tr_b16 v[212:213], v197 offset:0x2e00
	v_mfma_f32_16x16x32_bf16 v[244:247], v[138:141], v[248:251], v[244:247]
	s_waitcnt lgkmcnt(6)
	v_mfma_f32_32x32x16_bf16 v[50:65], v[134:137], v[198:201], v[50:65]
	v_cvt_pk_bf16_f32 v130, v90, v91
	ds_read_b64_tr_b16 v[214:215], v197 offset:0x3000
	ds_read_b64_tr_b16 v[216:217], v197 offset:0x3800
	s_waitcnt lgkmcnt(6)
	v_mfma_f32_32x32x16_bf16 v[34:49], v[134:137], v[202:205], v[34:49]
	v_cvt_pk_bf16_f32 v131, v92, v93
	ds_read_b64_tr_b16 v[218:219], v197 offset:0x3200
	ds_read_b64_tr_b16 v[220:221], v197 offset:0x3a00
	s_waitcnt lgkmcnt(6)
	v_mfma_f32_32x32x16_bf16 v[18:33], v[134:137], v[206:209], v[18:33]
	v_cvt_pk_bf16_f32 v132, v94, v95
	ds_read_b64_tr_b16 v[222:223], v197 offset:0x3400
	ds_read_b64_tr_b16 v[224:225], v197 offset:0x3c00
	s_waitcnt lgkmcnt(6)
	v_mfma_f32_32x32x16_bf16 v[2:17], v[134:137], v[210:213], v[2:17]
	v_cvt_pk_bf16_f32 v133, v96, v97
	ds_read_b64_tr_b16 v[226:227], v197 offset:0x3600
	ds_read_b64_tr_b16 v[228:229], v197 offset:0x3e00
	v_mfma_f32_16x16x32_bf16 v[244:247], v[134:137], v[248:251], v[244:247]
	s_waitcnt lgkmcnt(6)
	v_mfma_f32_32x32x16_bf16 v[50:65], v[130:133], v[214:217], v[50:65]
	ds_read_b128 v[82:85], v188 offset:32768
	ds_read_b128 v[198:201], v190 offset:32768
	s_waitcnt lgkmcnt(6)
	v_mfma_f32_32x32x16_bf16 v[34:49], v[130:133], v[218:221], v[34:49]
	ds_read_b128 v[202:205], v190 offset:36864
	s_waitcnt lgkmcnt(5)
	v_mfma_f32_32x32x16_bf16 v[18:33], v[130:133], v[222:225], v[18:33]
	ds_read_b128 v[206:209], v191 offset:32768
	s_waitcnt lgkmcnt(4)
	v_mfma_f32_32x32x16_bf16 v[2:17], v[130:133], v[226:229], v[2:17]
	ds_read_b128 v[210:213], v191 offset:36864
	v_mfma_f32_16x16x32_bf16 v[244:247], v[130:133], v[248:251], v[244:247]
	s_waitcnt lgkmcnt(4)
	v_mfma_f32_32x32x16_bf16 v[98:113], v[82:85], v[126:129], v[66:81]
	v_mfma_f32_32x32x16_bf16 v[82:97], v[230:233], v[126:129], v[66:81]
	v_mfma_f32_32x32x16_bf16 v[98:113], v[234:237], v[122:125], v[98:113]
	v_mfma_f32_32x32x16_bf16 v[82:97], v[238:241], v[122:125], v[82:97]
	s_waitcnt lgkmcnt(3)
	v_mfma_f32_32x32x16_bf16 v[98:113], v[198:201], v[118:121], v[98:113]
	s_waitcnt lgkmcnt(2)
	v_mfma_f32_32x32x16_bf16 v[82:97], v[202:205], v[118:121], v[82:97]
	s_waitcnt lgkmcnt(1)
	v_mfma_f32_32x32x16_bf16 v[98:113], v[206:209], v[114:117], v[98:113]
	s_waitcnt lgkmcnt(0)
	v_mfma_f32_32x32x16_bf16 v[82:97], v[210:213], v[114:117], v[82:97]
	s_and_b64 vcc, exec, s[6:7]
	s_cbranch_vccnz .LBB0_614
	s_waitcnt vmcnt(1)

.LBB0_625:
	v_mul_f32_e32 v242, v184, v194
	v_mul_f32_e32 v184, v242, v197
	s_add_i32 s96, s96, 2
	s_and_b64 vcc, exec, s[0:1]
	s_cbranch_vccnz .Lrot_da_exit
	s_mov_b32 s0, s12
	s_mov_b32 s12, s75
	s_mov_b32 s75, s74
	s_mov_b32 s74, s0
	v_add_u32_e32 v238, s74, v193
	s_branch .LBB0_599
.Lrot_da_exit:
	s_barrier
	v_cvt_pk_bf16_f32 v138, v106, v107
	v_cvt_pk_bf16_f32 v139, v108, v109
	v_cvt_pk_bf16_f32 v140, v110, v111
	v_cvt_pk_bf16_f32 v141, v112, v113
	v_cvt_pk_bf16_f32 v134, v82, v83
	v_cvt_pk_bf16_f32 v135, v84, v85
	v_cvt_pk_bf16_f32 v136, v86, v87
	v_cvt_pk_bf16_f32 v137, v88, v89
	v_cvt_pk_bf16_f32 v130, v90, v91
	v_cvt_pk_bf16_f32 v131, v92, v93
	v_cvt_pk_bf16_f32 v132, v94, v95
	v_cvt_pk_bf16_f32 v133, v96, v97
	s_nop 1
	v_mfma_f32_16x16x32_bf16 v[244:247], v[142:145], v[248:251], v[244:247]
	v_mfma_f32_16x16x32_bf16 v[244:247], v[138:141], v[248:251], v[244:247]
	v_mfma_f32_16x16x32_bf16 v[244:247], v[134:137], v[248:251], v[244:247]
	v_mfma_f32_16x16x32_bf16 v[244:247], v[130:133], v[248:251], v[244:247]
	s_branch .LBB0_629
